# v25 + HGRN chunk loop LDS fragment prefetch + attention epilogue weight loads hoisted / stores back to back
# speedup vs baseline: 1.0139x; 1.0139x over previous
; #define LAS __attribute__((address_space(3)))
; #define MFMA16(a, b, c) __builtin_amdgcn_mfma_f32_16x16x32_bf16((a), (b), (c), 0, 0, 0)
; DI void hgrn_item(const Params& p, const int ch) {
;     ...
;     {
;       const int sb = wid >> 1;
; #pragma unroll
;       for (int cbi = 0; cbi < 2; ++cbi) {
;         const int cb = (wid & 1) * 2 + cbi;
;         f32x4 acc = (f32x4){0.f, 0.f, 0.f, 0.f};
; #pragma unroll
;         for (int ks = 0; ks < 4; ++ks) {
;           const bf16x8 A = *(const LAS bf16x8*)(lds + HG_KT + (16 * sb + l15) * 272 + ks * 64 + fq * 16);
;           const bf16x8 B = *(const LAS bf16x8*)(lds + HG_QT + (16 * cb + l15) * 272 + ks * 64 + fq * 16);
;           acc = MFMA16(A, B, acc);
;         }
;         const int s0 = 16 * sb + 4 * fq, cc = 16 * cb + l15;
;         float m[4];
; #pragma unroll
;         for (int e = 0; e < 4; ++e) { const bool keep = dir ? (s0 + e >= cc) : (s0 + e <= cc); m[e] = keep ? acc[e] : 0.f; }
;         uint2 q; q.x = pk_bf16(m[0], m[1]); q.y = pk_bf16(m[2], m[3]);
;         *(uint2*)(shm_raw + HG_AM + cc * 144 + s0 * 2) = q;
;       }
;     }
;     __syncthreads();
;     bf16x8 vf[2];
; #pragma unroll
;     for (int st = 0; st < 2; ++st) vf[st] = *(const LAS bf16x8*)(lds + HG_VT + (it & 1) * 16384 + vrd + (((4 * st + fq) ^ swv) << 4));
;     bf16x8 Sb[4];
; #pragma unroll
;     for (int m = 0; m < 4; ++m) {
;       u32x4 pk;
;       pk[0] = pk_bf16(St[2 * m][0], St[2 * m][1]); pk[1] = pk_bf16(St[2 * m][2], St[2 * m][3]);
;       pk[2] = pk_bf16(St[2 * m + 1][0], St[2 * m + 1][1]); pk[3] = pk_bf16(St[2 * m + 1][2], St[2 * m + 1][3]);
;       Sb[m] = __builtin_bit_cast(bf16x8, pk);
;     }
; #pragma unroll
;     for (int cb = 0; cb < 4; ++cb) {
;       f32x4 acc = (f32x4){0.f, 0.f, 0.f, 0.f};
; #pragma unroll
;       for (int st = 0; st < 2; ++st) {
;         const bf16x8 B = *(const LAS bf16x8*)(lds + HG_AM + (16 * cb + l15) * 144 + st * 64 + fq * 16);
;         acc = MFMA16(vf[st], B, acc);
;       }
; #pragma unroll
;       for (int m = 0; m < 4; ++m) {
;         const s16x4 lo = *(const LAS s16x4*)(lds + HG_QT + (16 * cb + l15) * 272 + (32 * m + 4 * fq) * 2);
;         const s16x4 hi = *(const LAS s16x4*)(lds + HG_QT + (16 * cb + l15) * 272 + (32 * m + 16 + 4 * fq) * 2);
;         const bf16x8 B = __builtin_shufflevector(lo, hi, 0, 1, 2, 3, 4, 5, 6, 7);
;         acc = MFMA16(Sb[m], B, acc);
.LBB0_1002:
	ds_read_b128 v[32:35], v98 offset:17408
	ds_read_b128 v[36:39], v99
	s_add_i32 s84, s80, -1
	s_and_b64 s[42:43], s[4:5], exec
	s_cselect_b32 s41, s84, s41
	s_and_b32 s42, s96, 0x4000
	s_waitcnt lgkmcnt(0)
	v_mfma_f32_16x16x32_bf16 v[32:35], v[32:35], v[36:39], 0
	ds_read_b128 v[36:39], v98 offset:17472
	ds_read_b128 v[40:43], v99 offset:64
	v_cvt_pk_bf16_f32 v52, v4, v5
	v_cvt_pk_bf16_f32 v53, v6, v7
	v_cvt_pk_bf16_f32 v54, v0, v1
	s_waitcnt lgkmcnt(0)
	v_mfma_f32_16x16x32_bf16 v[32:35], v[36:39], v[40:43], v[32:35]
	ds_read_b128 v[36:39], v98 offset:17536
	ds_read_b128 v[40:43], v99 offset:128
	v_cvt_pk_bf16_f32 v55, v2, v3
	v_cvt_pk_bf16_f32 v48, v12, v13
	s_waitcnt lgkmcnt(0)
	v_mfma_f32_16x16x32_bf16 v[32:35], v[36:39], v[40:43], v[32:35]
	ds_read_b128 v[36:39], v98 offset:17600
	ds_read_b128 v[40:43], v99 offset:192
	v_cvt_pk_bf16_f32 v49, v14, v15
	v_cvt_pk_bf16_f32 v50, v8, v9
	s_waitcnt lgkmcnt(0)
	v_mfma_f32_16x16x32_bf16 v[32:35], v[36:39], v[40:43], v[32:35]
	v_cvt_pk_bf16_f32 v51, v10, v11
	v_cvt_pk_bf16_f32 v44, v20, v21
	v_cvt_pk_bf16_f32 v45, v22, v23
	s_nop 4
	v_cndmask_b32_e64 v32, 0, v32, s[22:23]
	v_cndmask_b32_e64 v33, 0, v33, s[24:25]
	v_cndmask_b32_e64 v34, 0, v34, s[26:27]
	v_cndmask_b32_e64 v35, 0, v35, s[28:29]
	v_cvt_pk_bf16_f32 v32, v32, v33
	v_cvt_pk_bf16_f32 v33, v34, v35
	ds_write_b64 v100, v[32:33] offset:53248
	ds_read_b128 v[32:35], v98 offset:17408
	ds_read_b128 v[36:39], v99 offset:4352
	s_waitcnt lgkmcnt(0)
	v_mfma_f32_16x16x32_bf16 v[32:35], v[32:35], v[36:39], 0
	ds_read_b128 v[36:39], v98 offset:17472
	ds_read_b128 v[40:43], v99 offset:4416
	v_cvt_pk_bf16_f32 v46, v16, v17
	v_cvt_pk_bf16_f32 v47, v18, v19
	s_waitcnt lgkmcnt(0)
	v_mfma_f32_16x16x32_bf16 v[32:35], v[36:39], v[40:43], v[32:35]
	ds_read_b128 v[36:39], v98 offset:17536
	ds_read_b128 v[40:43], v99 offset:4480
	v_lshl_or_b32 v66, s41, 6, v73
	v_ashrrev_i32_e32 v67, 31, v66
	s_waitcnt lgkmcnt(0)
	v_mfma_f32_16x16x32_bf16 v[32:35], v[36:39], v[40:43], v[32:35]
	ds_read_b128 v[36:39], v98 offset:17600
	ds_read_b128 v[40:43], v99 offset:4544
	s_add_i32 s80, s80, 1
	s_cmp_eq_u32 s45, -1
	s_waitcnt lgkmcnt(0)
	v_mfma_f32_16x16x32_bf16 v[32:35], v[36:39], v[40:43], v[32:35]
	v_cvt_pk_bf16_f32 v40, v24, v25
	v_cvt_pk_bf16_f32 v41, v26, v27
	v_cvt_pk_bf16_f32 v42, v28, v29
	s_nop 4
	v_cndmask_b32_e64 v32, 0, v32, s[30:31]
	v_cndmask_b32_e64 v33, 0, v33, s[34:35]
	v_cndmask_b32_e64 v34, 0, v34, s[36:37]
	v_cndmask_b32_e64 v35, 0, v35, s[38:39]
	v_cvt_pk_bf16_f32 v32, v32, v33
	v_cvt_pk_bf16_f32 v33, v34, v35
	ds_write_b64 v100, v[32:33] offset:55552
	v_add_u32_e32 v32, s42, v85
	v_add_u32_e32 v33, v32, v95
	s_waitcnt lgkmcnt(0)
	s_barrier
	ds_read_b128 v[36:39], v33
	v_add_u32_e32 v32, v32, v96
	ds_read_b128 v[32:35], v32
	v_cvt_pk_bf16_f32 v43, v30, v31
	s_mov_b32 s96, s40
	s_mov_b32 s41, s45
	v_add_u32_e32 v190, 0x1000, v102
	v_add_u32_e32 v191, 0x2000, v102
	v_add_u32_e32 v234, 0x3000, v102
	ds_read_b128 v[218:221], v101 offset:53248
	ds_read_b128 v[222:225], v101 offset:53312
	ds_read2_b64 v[226:229], v102 offset0:0 offset1:4
	ds_read2_b64 v[230:233], v102 offset0:8 offset1:12
	ds_read2_b64 v[238:241], v102 offset0:16 offset1:20
	ds_read2_b64 v[242:245], v102 offset0:24 offset1:28
	ds_read_b128 v[166:169], v101 offset:55552
	ds_read_b128 v[170:173], v101 offset:55616
	ds_read2_b64 v[174:177], v190 offset0:32 offset1:36
	ds_read2_b64 v[178:181], v190 offset0:40 offset1:44
	ds_read2_b64 v[182:185], v190 offset0:48 offset1:52
	ds_read2_b64 v[186:189], v190 offset0:56 offset1:60
	s_waitcnt lgkmcnt(13)
	s_waitcnt lgkmcnt(11)
	v_mfma_f32_16x16x32_bf16 v[68:71], v[36:39], v[218:221], 0
	s_waitcnt lgkmcnt(10)
	v_mfma_f32_16x16x32_bf16 v[68:71], v[32:35], v[222:225], v[68:71]
	s_waitcnt lgkmcnt(9)
	v_mfma_f32_16x16x32_bf16 v[68:71], v[52:55], v[226:229], v[68:71]
	s_waitcnt lgkmcnt(8)
	v_mfma_f32_16x16x32_bf16 v[68:71], v[48:51], v[230:233], v[68:71]
	s_waitcnt lgkmcnt(7)
	v_mfma_f32_16x16x32_bf16 v[68:71], v[44:47], v[238:241], v[68:71]
	s_waitcnt lgkmcnt(6)
	v_mfma_f32_16x16x32_bf16 v[68:71], v[40:43], v[242:245], v[68:71]
	ds_read_b128 v[218:221], v101 offset:57856
	ds_read_b128 v[222:225], v101 offset:57920
	ds_read2_b64 v[226:229], v191 offset0:64 offset1:68
	ds_read2_b64 v[230:233], v191 offset0:72 offset1:76
	ds_read2_b64 v[238:241], v191 offset0:80 offset1:84
	ds_read2_b64 v[242:245], v191 offset0:88 offset1:92
	s_nop 1
	v_cvt_pk_bf16_f32 v246, v68, v69
	v_cvt_pk_bf16_f32 v247, v70, v71
	v_lshlrev_b64 v[248:249], 10, v[66:67]
	v_lshl_add_u64 v[248:249], v[64:65], 0, v[248:249]
	global_store_dwordx2 v[248:249], v[246:247], off
	s_waitcnt lgkmcnt(11)
	v_mfma_f32_16x16x32_bf16 v[68:71], v[36:39], v[166:169], 0
	s_waitcnt lgkmcnt(10)
	v_mfma_f32_16x16x32_bf16 v[68:71], v[32:35], v[170:173], v[68:71]
	s_waitcnt lgkmcnt(9)
	v_mfma_f32_16x16x32_bf16 v[68:71], v[52:55], v[174:177], v[68:71]
	s_waitcnt lgkmcnt(8)
	v_mfma_f32_16x16x32_bf16 v[68:71], v[48:51], v[178:181], v[68:71]
	s_waitcnt lgkmcnt(7)
	v_mfma_f32_16x16x32_bf16 v[68:71], v[44:47], v[182:185], v[68:71]
	s_waitcnt lgkmcnt(6)
; #define LAS __attribute__((address_space(3)))
; DI unsigned pk_bf16(float lo, float hi) { f32x2 v = {lo, hi}; return __builtin_bit_cast(unsigned, __builtin_convertvector(v, bf16x2_t)); }
; #define MFMA16(a, b, c) __builtin_amdgcn_mfma_f32_16x16x32_bf16((a), (b), (c), 0, 0, 0)
; DI void hgrn_item(const Params& p, const int ch) {
;     ...
; #pragma unroll
;     for (int cb = 0; cb < 4; ++cb) {
;       f32x4 acc = (f32x4){0.f, 0.f, 0.f, 0.f};
; #pragma unroll
;       for (int st = 0; st < 2; ++st) {
;         const bf16x8 B = *(const LAS bf16x8*)(lds + HG_AM + (16 * cb + l15) * 144 + st * 64 + fq * 16);
;         acc = MFMA16(vf[st], B, acc);
;       }
; #pragma unroll
;       for (int m = 0; m < 4; ++m) {
;         const s16x4 lo = *(const LAS s16x4*)(lds + HG_QT + (16 * cb + l15) * 272 + (32 * m + 4 * fq) * 2);
;         const s16x4 hi = *(const LAS s16x4*)(lds + HG_QT + (16 * cb + l15) * 272 + (32 * m + 16 + 4 * fq) * 2);
;         const bf16x8 B = __builtin_shufflevector(lo, hi, 0, 1, 2, 3, 4, 5, 6, 7);
;         acc = MFMA16(Sb[m], B, acc);
;       }
;       uint2 o; o.x = pk_bf16(acc[0], acc[1]); o.y = pk_bf16(acc[2], acc[3]);
;       *(uint2*)(Od + (size_t)(t0 + 16 * cb + l15) * 512) = o;
;     }
; #pragma unroll
;     for (int kb = 0; kb < 8; ++kb) {
;       const float4 dc = *(const float4*)(shm_raw + HG_DEC + (16 * kb + 4 * fq) * 4);
;       f32x4 s = St[kb];
;       s[0] *= dc.x; s[1] *= dc.y; s[2] *= dc.z; s[3] *= dc.w;
; #pragma unroll
;       for (int st = 0; st < 2; ++st) {
;         const bf16x8 A = *(const LAS bf16x8*)(lds + HG_KST + (16 * kb + l15) * 144 + st * 64 + fq * 16);
;         s = MFMA16(A, vf[st], s);
;       }
;       St[kb] = s;
;     }
;     __syncthreads();
	v_mfma_f32_16x16x32_bf16 v[68:71], v[40:43], v[186:189], v[68:71]
	ds_read_b128 v[166:169], v101 offset:60160
	ds_read_b128 v[170:173], v101 offset:60224
	ds_read2_b64 v[174:177], v234 offset0:96 offset1:100
	ds_read2_b64 v[178:181], v234 offset0:104 offset1:108
	ds_read2_b64 v[182:185], v234 offset0:112 offset1:116
	ds_read2_b64 v[186:189], v234 offset0:120 offset1:124
	s_nop 1
	v_cvt_pk_bf16_f32 v250, v68, v69
	v_cvt_pk_bf16_f32 v251, v70, v71
	v_or_b32_e32 v248, 16, v66
	v_ashrrev_i32_e32 v249, 31, v248
	v_lshlrev_b64 v[248:249], 10, v[248:249]
	v_lshl_add_u64 v[248:249], v[64:65], 0, v[248:249]
	global_store_dwordx2 v[248:249], v[250:251], off
	s_waitcnt lgkmcnt(11)
	v_mfma_f32_16x16x32_bf16 v[68:71], v[36:39], v[218:221], 0
	s_waitcnt lgkmcnt(10)
	v_mfma_f32_16x16x32_bf16 v[68:71], v[32:35], v[222:225], v[68:71]
	s_waitcnt lgkmcnt(9)
	v_mfma_f32_16x16x32_bf16 v[68:71], v[52:55], v[226:229], v[68:71]
	s_waitcnt lgkmcnt(8)
	v_mfma_f32_16x16x32_bf16 v[68:71], v[48:51], v[230:233], v[68:71]
	s_waitcnt lgkmcnt(7)
	v_mfma_f32_16x16x32_bf16 v[68:71], v[44:47], v[238:241], v[68:71]
	s_waitcnt lgkmcnt(6)
	v_mfma_f32_16x16x32_bf16 v[68:71], v[40:43], v[242:245], v[68:71]
	ds_read_b128 v[218:221], v86 offset:62464
	ds_read_b128 v[222:225], v101 offset:34816
	ds_read_b128 v[226:229], v101 offset:34880
	ds_read_b128 v[230:233], v86 offset:62528
	ds_read_b128 v[238:241], v101 offset:37120
	ds_read_b128 v[242:245], v101 offset:37184
	s_nop 1
	v_cvt_pk_bf16_f32 v246, v68, v69
	v_cvt_pk_bf16_f32 v247, v70, v71
	v_or_b32_e32 v248, 32, v66
	v_ashrrev_i32_e32 v249, 31, v248
	v_lshlrev_b64 v[248:249], 10, v[248:249]
	v_lshl_add_u64 v[248:249], v[64:65], 0, v[248:249]
	global_store_dwordx2 v[248:249], v[246:247], off
	s_waitcnt lgkmcnt(11)
	v_mfma_f32_16x16x32_bf16 v[68:71], v[36:39], v[166:169], 0
	s_waitcnt lgkmcnt(10)
	v_mfma_f32_16x16x32_bf16 v[68:71], v[32:35], v[170:173], v[68:71]
	s_waitcnt lgkmcnt(9)
	v_mfma_f32_16x16x32_bf16 v[68:71], v[52:55], v[174:177], v[68:71]
	s_waitcnt lgkmcnt(8)
	v_mfma_f32_16x16x32_bf16 v[68:71], v[48:51], v[178:181], v[68:71]
	s_waitcnt lgkmcnt(7)
	v_mfma_f32_16x16x32_bf16 v[68:71], v[44:47], v[182:185], v[68:71]
	s_waitcnt lgkmcnt(6)
	v_mfma_f32_16x16x32_bf16 v[68:71], v[40:43], v[186:189], v[68:71]
	ds_read_b128 v[166:169], v86 offset:62592
	ds_read_b128 v[170:173], v101 offset:39424
	ds_read_b128 v[174:177], v101 offset:39488
	ds_read_b128 v[178:181], v86 offset:62656
	ds_read_b128 v[182:185], v101 offset:41728
	ds_read_b128 v[186:189], v101 offset:41792
	s_nop 1
	v_cvt_pk_bf16_f32 v250, v68, v69
	v_cvt_pk_bf16_f32 v251, v70, v71
	v_or_b32_e32 v248, 48, v66
	v_ashrrev_i32_e32 v249, 31, v248
	v_lshlrev_b64 v[248:249], 10, v[248:249]
	v_lshl_add_u64 v[248:249], v[64:65], 0, v[248:249]
	global_store_dwordx2 v[248:249], v[250:251], off
	s_waitcnt lgkmcnt(11)
	v_pk_mul_f32 v[4:5], v[4:5], v[218:219]
	v_pk_mul_f32 v[6:7], v[6:7], v[220:221]
	s_waitcnt lgkmcnt(10)
	s_waitcnt lgkmcnt(9)
	s_nop 1
	v_mfma_f32_16x16x32_bf16 v[4:7], v[222:225], v[36:39], v[4:7]
	v_mfma_f32_16x16x32_bf16 v[4:7], v[226:229], v[32:35], v[4:7]
	ds_read_b128 v[218:221], v86 offset:62720
	ds_read_b128 v[222:225], v101 offset:44032
	ds_read_b128 v[226:229], v101 offset:44096
	s_waitcnt lgkmcnt(11)
	v_pk_mul_f32 v[0:1], v[0:1], v[230:231]
	v_pk_mul_f32 v[2:3], v[2:3], v[232:233]
	s_waitcnt lgkmcnt(10)
	s_waitcnt lgkmcnt(9)
	s_nop 1
	v_mfma_f32_16x16x32_bf16 v[0:3], v[238:241], v[36:39], v[0:3]
	v_mfma_f32_16x16x32_bf16 v[0:3], v[242:245], v[32:35], v[0:3]
	ds_read_b128 v[230:233], v86 offset:62784
	ds_read_b128 v[238:241], v101 offset:46336
	ds_read_b128 v[242:245], v101 offset:46400
	s_waitcnt lgkmcnt(11)
	v_pk_mul_f32 v[12:13], v[12:13], v[166:167]
	v_pk_mul_f32 v[14:15], v[14:15], v[168:169]
	s_waitcnt lgkmcnt(10)
	s_waitcnt lgkmcnt(9)
	s_nop 1
	v_mfma_f32_16x16x32_bf16 v[12:15], v[170:173], v[36:39], v[12:15]
	v_mfma_f32_16x16x32_bf16 v[12:15], v[174:177], v[32:35], v[12:15]
	ds_read_b128 v[166:169], v86 offset:62848
	ds_read_b128 v[170:173], v101 offset:48640
	ds_read_b128 v[174:177], v101 offset:48704
	s_waitcnt lgkmcnt(11)
	v_pk_mul_f32 v[8:9], v[8:9], v[178:179]
	v_pk_mul_f32 v[10:11], v[10:11], v[180:181]
	s_waitcnt lgkmcnt(10)
	s_waitcnt lgkmcnt(9)
	s_nop 1
	v_mfma_f32_16x16x32_bf16 v[8:11], v[182:185], v[36:39], v[8:11]
	v_mfma_f32_16x16x32_bf16 v[8:11], v[186:189], v[32:35], v[8:11]
	ds_read_b128 v[178:181], v86 offset:62912
	ds_read_b128 v[182:185], v101 offset:50944
	ds_read_b128 v[186:189], v101 offset:51008
	s_waitcnt lgkmcnt(11)
	v_pk_mul_f32 v[20:21], v[20:21], v[218:219]
	v_pk_mul_f32 v[22:23], v[22:23], v[220:221]
	s_waitcnt lgkmcnt(10)
	s_waitcnt lgkmcnt(9)
	s_nop 1
	v_mfma_f32_16x16x32_bf16 v[20:23], v[222:225], v[36:39], v[20:23]
	v_mfma_f32_16x16x32_bf16 v[20:23], v[226:229], v[32:35], v[20:23]
	s_waitcnt lgkmcnt(8)
	v_pk_mul_f32 v[16:17], v[16:17], v[230:231]
	v_pk_mul_f32 v[18:19], v[18:19], v[232:233]
	s_waitcnt lgkmcnt(7)
	s_waitcnt lgkmcnt(6)
	s_nop 1
	v_mfma_f32_16x16x32_bf16 v[16:19], v[238:241], v[36:39], v[16:19]
	v_mfma_f32_16x16x32_bf16 v[16:19], v[242:245], v[32:35], v[16:19]
	s_waitcnt lgkmcnt(5)
	v_pk_mul_f32 v[24:25], v[24:25], v[166:167]
	v_pk_mul_f32 v[26:27], v[26:27], v[168:169]
	s_waitcnt lgkmcnt(4)
	s_waitcnt lgkmcnt(3)
	s_nop 1
	v_mfma_f32_16x16x32_bf16 v[24:27], v[170:173], v[36:39], v[24:27]
	v_mfma_f32_16x16x32_bf16 v[24:27], v[174:177], v[32:35], v[24:27]
	s_waitcnt lgkmcnt(2)
	v_pk_mul_f32 v[28:29], v[28:29], v[178:179]
	v_pk_mul_f32 v[30:31], v[30:31], v[180:181]
	s_waitcnt lgkmcnt(1)
	s_waitcnt lgkmcnt(0)
	s_nop 1
	s_waitcnt lgkmcnt(0)
	s_barrier
	v_mfma_f32_16x16x32_bf16 v[28:31], v[182:185], v[36:39], v[28:31]
	v_mfma_f32_16x16x32_bf16 v[28:31], v[186:189], v[32:35], v[28:31]
	s_cbranch_scc1 .Lhg_done
